# pooling mixer GEMM: the 16 weight fragments requested before the loop's barrier, loop written out 4x (was 4 loads + wait per trip)
# baseline (speedup 1.0000x reference)
.LBB0_619:
	s_or_b64 exec, exec, s[8:9]
	s_and_b32 s2, s26, 3
	s_lshl_b32 s2, s2, 17
	v_mov_b32_e32 v26, 0
	v_lshl_add_u64 v[66:67], v[80:81], 0, s[2:3]
	v_lshl_add_u64 v[68:69], v[82:83], 0, s[2:3]
	s_mov_b64 s[4:5], 0
	v_mov_b32_e32 v70, v104
	v_mov_b32_e32 v27, v26
	v_mov_b32_e32 v28, v26
	v_mov_b32_e32 v29, v26
	v_mov_b32_e32 v42, v26
	v_mov_b32_e32 v43, v26
	v_mov_b32_e32 v44, v26
	v_mov_b32_e32 v45, v26
	v_mov_b32_e32 v46, v26
	v_mov_b32_e32 v47, v26
	v_mov_b32_e32 v48, v26
	v_mov_b32_e32 v49, v26
	v_mov_b32_e32 v58, v26
	v_mov_b32_e32 v59, v26
	v_mov_b32_e32 v60, v26
	v_mov_b32_e32 v61, v26
	v_mov_b32_e32 v2, v26
	v_mov_b32_e32 v3, v26
	v_mov_b32_e32 v4, v26
	v_mov_b32_e32 v5, v26
	v_mov_b32_e32 v6, v26
	v_mov_b32_e32 v7, v26
	v_mov_b32_e32 v8, v26
	v_mov_b32_e32 v9, v26
	v_mov_b32_e32 v18, v26
	v_mov_b32_e32 v19, v26
	v_mov_b32_e32 v20, v26
	v_mov_b32_e32 v21, v26
	v_mov_b32_e32 v30, v26
	v_mov_b32_e32 v31, v26
	v_mov_b32_e32 v32, v26
	v_mov_b32_e32 v33, v26
	v_mov_b32_e32 v38, v26
	v_mov_b32_e32 v39, v26
	v_mov_b32_e32 v40, v26
	v_mov_b32_e32 v41, v26
	v_mov_b32_e32 v50, v26
	v_mov_b32_e32 v51, v26
	v_mov_b32_e32 v52, v26
	v_mov_b32_e32 v53, v26
	v_mov_b32_e32 v54, v26
	v_mov_b32_e32 v55, v26
	v_mov_b32_e32 v56, v26
	v_mov_b32_e32 v57, v26
	v_mov_b32_e32 v62, v26
	v_mov_b32_e32 v63, v26
	v_mov_b32_e32 v64, v26
	v_mov_b32_e32 v65, v26
	v_mov_b32_e32 v34, v26
	v_mov_b32_e32 v35, v26
	v_mov_b32_e32 v36, v26
	v_mov_b32_e32 v37, v26
	v_mov_b32_e32 v22, v26
	v_mov_b32_e32 v23, v26
	v_mov_b32_e32 v24, v26
	v_mov_b32_e32 v25, v26
	v_mov_b32_e32 v10, v26
	v_mov_b32_e32 v11, v26
	v_mov_b32_e32 v12, v26
	v_mov_b32_e32 v13, v26
	v_mov_b32_e32 v14, v26
	v_mov_b32_e32 v15, v26
	v_mov_b32_e32 v16, v26
	v_mov_b32_e32 v17, v26
	v_add_co_u32_e32 v232, vcc, s23, v68
	s_nop 1
	v_addc_co_u32_e32 v233, vcc, 0, v69, vcc
	v_add_co_u32_e32 v234, vcc, s23, v66
	s_nop 1
	v_addc_co_u32_e32 v235, vcc, 0, v67, vcc
	global_load_dwordx4 v[144:147], v[232:233], off
	global_load_dwordx4 v[148:151], v[234:235], off
	global_load_dwordx4 v[152:155], v[232:233], off offset:64
	global_load_dwordx4 v[156:159], v[234:235], off offset:64
	global_load_dwordx4 v[160:163], v[232:233], off offset:128
	global_load_dwordx4 v[164:167], v[234:235], off offset:128
	global_load_dwordx4 v[168:171], v[232:233], off offset:192
	global_load_dwordx4 v[172:175], v[234:235], off offset:192
	global_load_dwordx4 v[200:203], v[232:233], off offset:256
	global_load_dwordx4 v[204:207], v[234:235], off offset:256
	global_load_dwordx4 v[208:211], v[232:233], off offset:320
	global_load_dwordx4 v[212:215], v[234:235], off offset:320
	global_load_dwordx4 v[216:219], v[232:233], off offset:384
	global_load_dwordx4 v[220:223], v[234:235], off offset:384
	global_load_dwordx4 v[224:227], v[232:233], off offset:448
	global_load_dwordx4 v[228:231], v[234:235], off offset:448
	s_waitcnt lgkmcnt(0)
	s_barrier
.LBB0_620:
	s_waitcnt vmcnt(0)
	v_lshl_add_u64 v[72:73], v[68:69], 0, s[4:5]
	v_add_co_u32_e32 v72, vcc, s23, v72
	v_lshl_add_u64 v[92:93], v[66:67], 0, s[4:5]
	s_nop 0
	v_addc_co_u32_e32 v73, vcc, 0, v73, vcc
	v_add_co_u32_e32 v110, vcc, s23, v92
	ds_read_b128 v[84:87], v70
	ds_read_b128 v[88:91], v70 offset:64
	v_addc_co_u32_e32 v111, vcc, 0, v93, vcc
	v_mov_b32_e32 v92, v144
	v_mov_b32_e32 v93, v145
	v_mov_b32_e32 v94, v146
	v_mov_b32_e32 v95, v147
	v_mov_b32_e32 v96, v148
	v_mov_b32_e32 v97, v149
	v_mov_b32_e32 v98, v150
	v_mov_b32_e32 v99, v151
	v_mov_b32_e32 v100, v152
	v_mov_b32_e32 v101, v153
	v_mov_b32_e32 v102, v154
	v_mov_b32_e32 v103, v155
	s_add_u32 s4, s4, 0x80
	v_mov_b32_e32 v110, v156
	v_mov_b32_e32 v111, v157
	v_mov_b32_e32 v112, v158
	v_mov_b32_e32 v113, v159
	s_addc_u32 s5, s5, 0
	s_cmpk_lg_i32 s4, 0x200
	s_waitcnt lgkmcnt(1)
	v_mfma_f32_16x16x32_bf16 v[62:65], v[92:95], v[84:87], v[62:65]
	v_mfma_f32_16x16x32_bf16 v[58:61], v[96:99], v[84:87], v[58:61]
	ds_read_b128 v[84:87], v70 offset:8448
	ds_read_b128 v[114:117], v70 offset:8512
	s_waitcnt lgkmcnt(1)
	v_mfma_f32_16x16x32_bf16 v[54:57], v[92:95], v[84:87], v[54:57]
	v_mfma_f32_16x16x32_bf16 v[46:49], v[96:99], v[84:87], v[46:49]
	ds_read_b128 v[84:87], v70 offset:16896
	ds_read_b128 v[118:121], v70 offset:16960
	s_waitcnt lgkmcnt(1)
	v_mfma_f32_16x16x32_bf16 v[50:53], v[92:95], v[84:87], v[50:53]
	v_mfma_f32_16x16x32_bf16 v[42:45], v[96:99], v[84:87], v[42:45]
	ds_read_b128 v[84:87], v70 offset:25344
	ds_read_b128 v[122:125], v70 offset:25408
	s_waitcnt lgkmcnt(1)
	v_mfma_f32_16x16x32_bf16 v[38:41], v[92:95], v[84:87], v[38:41]
	v_mfma_f32_16x16x32_bf16 v[26:29], v[96:99], v[84:87], v[26:29]
	ds_read_b128 v[84:87], v70 offset:33792
	ds_read_b128 v[126:129], v70 offset:33856
	s_waitcnt lgkmcnt(1)
	v_mfma_f32_16x16x32_bf16 v[30:33], v[92:95], v[84:87], v[30:33]
	v_mfma_f32_16x16x32_bf16 v[34:37], v[96:99], v[84:87], v[34:37]
	ds_read_b128 v[84:87], v70 offset:42240
	ds_read_b128 v[130:133], v70 offset:42304
	s_waitcnt lgkmcnt(1)
	v_mfma_f32_16x16x32_bf16 v[18:21], v[92:95], v[84:87], v[18:21]
	v_mfma_f32_16x16x32_bf16 v[22:25], v[96:99], v[84:87], v[22:25]
	ds_read_b128 v[84:87], v70 offset:50688
	ds_read_b128 v[134:137], v70 offset:50752
	s_waitcnt lgkmcnt(1)
	v_mfma_f32_16x16x32_bf16 v[6:9], v[92:95], v[84:87], v[6:9]
	v_mfma_f32_16x16x32_bf16 v[10:13], v[96:99], v[84:87], v[10:13]
	ds_read_b128 v[84:87], v70 offset:59136
	ds_read_b128 v[138:141], v70 offset:59200
	v_add_u32_e32 v70, 0x80, v70
	s_waitcnt lgkmcnt(1)
	v_mfma_f32_16x16x32_bf16 v[2:5], v[92:95], v[84:87], v[2:5]
	v_mfma_f32_16x16x32_bf16 v[14:17], v[96:99], v[84:87], v[14:17]
	v_mfma_f32_16x16x32_bf16 v[62:65], v[100:103], v[88:91], v[62:65]
	v_mfma_f32_16x16x32_bf16 v[58:61], v[110:113], v[88:91], v[58:61]
	v_mfma_f32_16x16x32_bf16 v[54:57], v[100:103], v[114:117], v[54:57]
	v_mfma_f32_16x16x32_bf16 v[46:49], v[110:113], v[114:117], v[46:49]
	v_mfma_f32_16x16x32_bf16 v[50:53], v[100:103], v[118:121], v[50:53]
	v_mfma_f32_16x16x32_bf16 v[42:45], v[110:113], v[118:121], v[42:45]
	v_mfma_f32_16x16x32_bf16 v[38:41], v[100:103], v[122:125], v[38:41]
	v_mfma_f32_16x16x32_bf16 v[26:29], v[110:113], v[122:125], v[26:29]
	v_mfma_f32_16x16x32_bf16 v[30:33], v[100:103], v[126:129], v[30:33]
	v_mfma_f32_16x16x32_bf16 v[34:37], v[110:113], v[126:129], v[34:37]
	v_mfma_f32_16x16x32_bf16 v[18:21], v[100:103], v[130:133], v[18:21]
	v_mfma_f32_16x16x32_bf16 v[22:25], v[110:113], v[130:133], v[22:25]
	v_mfma_f32_16x16x32_bf16 v[6:9], v[100:103], v[134:137], v[6:9]
	v_mfma_f32_16x16x32_bf16 v[10:13], v[110:113], v[134:137], v[10:13]
	s_waitcnt lgkmcnt(0)
	v_mfma_f32_16x16x32_bf16 v[2:5], v[100:103], v[138:141], v[2:5]
	v_mfma_f32_16x16x32_bf16 v[14:17], v[110:113], v[138:141], v[14:17]
	v_lshl_add_u64 v[72:73], v[68:69], 0, s[4:5]
	v_add_co_u32_e32 v72, vcc, s23, v72
	v_lshl_add_u64 v[92:93], v[66:67], 0, s[4:5]
	s_nop 0
	v_addc_co_u32_e32 v73, vcc, 0, v73, vcc
	v_add_co_u32_e32 v110, vcc, s23, v92
	ds_read_b128 v[84:87], v70
	ds_read_b128 v[88:91], v70 offset:64
	v_addc_co_u32_e32 v111, vcc, 0, v93, vcc
	v_mov_b32_e32 v92, v160
	v_mov_b32_e32 v93, v161
	v_mov_b32_e32 v94, v162
	v_mov_b32_e32 v95, v163
	v_mov_b32_e32 v96, v164
	v_mov_b32_e32 v97, v165
	v_mov_b32_e32 v98, v166
	v_mov_b32_e32 v99, v167
	v_mov_b32_e32 v100, v168
	v_mov_b32_e32 v101, v169
	v_mov_b32_e32 v102, v170
	v_mov_b32_e32 v103, v171
	s_add_u32 s4, s4, 0x80
	v_mov_b32_e32 v110, v172
	v_mov_b32_e32 v111, v173
	v_mov_b32_e32 v112, v174
	v_mov_b32_e32 v113, v175
	s_addc_u32 s5, s5, 0
	s_cmpk_lg_i32 s4, 0x200
	s_waitcnt lgkmcnt(1)
	v_mfma_f32_16x16x32_bf16 v[62:65], v[92:95], v[84:87], v[62:65]
	v_mfma_f32_16x16x32_bf16 v[58:61], v[96:99], v[84:87], v[58:61]
	ds_read_b128 v[84:87], v70 offset:8448
	ds_read_b128 v[114:117], v70 offset:8512
	s_waitcnt lgkmcnt(1)
	v_mfma_f32_16x16x32_bf16 v[54:57], v[92:95], v[84:87], v[54:57]
	v_mfma_f32_16x16x32_bf16 v[46:49], v[96:99], v[84:87], v[46:49]
	ds_read_b128 v[84:87], v70 offset:16896
	ds_read_b128 v[118:121], v70 offset:16960
	s_waitcnt lgkmcnt(1)
	v_mfma_f32_16x16x32_bf16 v[50:53], v[92:95], v[84:87], v[50:53]
	v_mfma_f32_16x16x32_bf16 v[42:45], v[96:99], v[84:87], v[42:45]
	ds_read_b128 v[84:87], v70 offset:25344
	ds_read_b128 v[122:125], v70 offset:25408
	s_waitcnt lgkmcnt(1)
	v_mfma_f32_16x16x32_bf16 v[38:41], v[92:95], v[84:87], v[38:41]
	v_mfma_f32_16x16x32_bf16 v[26:29], v[96:99], v[84:87], v[26:29]
	ds_read_b128 v[84:87], v70 offset:33792
	ds_read_b128 v[126:129], v70 offset:33856
	s_waitcnt lgkmcnt(1)
	v_mfma_f32_16x16x32_bf16 v[30:33], v[92:95], v[84:87], v[30:33]
	v_mfma_f32_16x16x32_bf16 v[34:37], v[96:99], v[84:87], v[34:37]
	ds_read_b128 v[84:87], v70 offset:42240
	ds_read_b128 v[130:133], v70 offset:42304
	s_waitcnt lgkmcnt(1)
	v_mfma_f32_16x16x32_bf16 v[18:21], v[92:95], v[84:87], v[18:21]
	v_mfma_f32_16x16x32_bf16 v[22:25], v[96:99], v[84:87], v[22:25]
	ds_read_b128 v[84:87], v70 offset:50688
	ds_read_b128 v[134:137], v70 offset:50752
	s_waitcnt lgkmcnt(1)
	v_mfma_f32_16x16x32_bf16 v[6:9], v[92:95], v[84:87], v[6:9]
	v_mfma_f32_16x16x32_bf16 v[10:13], v[96:99], v[84:87], v[10:13]
	ds_read_b128 v[84:87], v70 offset:59136
	ds_read_b128 v[138:141], v70 offset:59200
	v_add_u32_e32 v70, 0x80, v70
	s_waitcnt lgkmcnt(1)
	v_mfma_f32_16x16x32_bf16 v[2:5], v[92:95], v[84:87], v[2:5]
	v_mfma_f32_16x16x32_bf16 v[14:17], v[96:99], v[84:87], v[14:17]
	v_mfma_f32_16x16x32_bf16 v[62:65], v[100:103], v[88:91], v[62:65]
	v_mfma_f32_16x16x32_bf16 v[58:61], v[110:113], v[88:91], v[58:61]
	v_mfma_f32_16x16x32_bf16 v[54:57], v[100:103], v[114:117], v[54:57]
	v_mfma_f32_16x16x32_bf16 v[46:49], v[110:113], v[114:117], v[46:49]
	v_mfma_f32_16x16x32_bf16 v[50:53], v[100:103], v[118:121], v[50:53]
	v_mfma_f32_16x16x32_bf16 v[42:45], v[110:113], v[118:121], v[42:45]
	v_mfma_f32_16x16x32_bf16 v[38:41], v[100:103], v[122:125], v[38:41]
	v_mfma_f32_16x16x32_bf16 v[26:29], v[110:113], v[122:125], v[26:29]
	v_mfma_f32_16x16x32_bf16 v[30:33], v[100:103], v[126:129], v[30:33]
	v_mfma_f32_16x16x32_bf16 v[34:37], v[110:113], v[126:129], v[34:37]
	v_mfma_f32_16x16x32_bf16 v[18:21], v[100:103], v[130:133], v[18:21]
	v_mfma_f32_16x16x32_bf16 v[22:25], v[110:113], v[130:133], v[22:25]
	v_mfma_f32_16x16x32_bf16 v[6:9], v[100:103], v[134:137], v[6:9]
	v_mfma_f32_16x16x32_bf16 v[10:13], v[110:113], v[134:137], v[10:13]
	s_waitcnt lgkmcnt(0)
	v_mfma_f32_16x16x32_bf16 v[2:5], v[100:103], v[138:141], v[2:5]
	v_mfma_f32_16x16x32_bf16 v[14:17], v[110:113], v[138:141], v[14:17]
	v_lshl_add_u64 v[72:73], v[68:69], 0, s[4:5]
	v_add_co_u32_e32 v72, vcc, s23, v72
	v_lshl_add_u64 v[92:93], v[66:67], 0, s[4:5]
	s_nop 0
	v_addc_co_u32_e32 v73, vcc, 0, v73, vcc
	v_add_co_u32_e32 v110, vcc, s23, v92
	ds_read_b128 v[84:87], v70
	ds_read_b128 v[88:91], v70 offset:64
	v_addc_co_u32_e32 v111, vcc, 0, v93, vcc
	v_mov_b32_e32 v92, v200
	v_mov_b32_e32 v93, v201
	v_mov_b32_e32 v94, v202
	v_mov_b32_e32 v95, v203
	v_mov_b32_e32 v96, v204
	v_mov_b32_e32 v97, v205
	v_mov_b32_e32 v98, v206
	v_mov_b32_e32 v99, v207
	v_mov_b32_e32 v100, v208
	v_mov_b32_e32 v101, v209
	v_mov_b32_e32 v102, v210
	v_mov_b32_e32 v103, v211
	s_add_u32 s4, s4, 0x80
	v_mov_b32_e32 v110, v212
	v_mov_b32_e32 v111, v213
	v_mov_b32_e32 v112, v214
	v_mov_b32_e32 v113, v215
	s_addc_u32 s5, s5, 0
	s_cmpk_lg_i32 s4, 0x200
	s_waitcnt lgkmcnt(1)
	v_mfma_f32_16x16x32_bf16 v[62:65], v[92:95], v[84:87], v[62:65]
	v_mfma_f32_16x16x32_bf16 v[58:61], v[96:99], v[84:87], v[58:61]
	ds_read_b128 v[84:87], v70 offset:8448
	ds_read_b128 v[114:117], v70 offset:8512
	s_waitcnt lgkmcnt(1)
	v_mfma_f32_16x16x32_bf16 v[54:57], v[92:95], v[84:87], v[54:57]
	v_mfma_f32_16x16x32_bf16 v[46:49], v[96:99], v[84:87], v[46:49]
	ds_read_b128 v[84:87], v70 offset:16896
	ds_read_b128 v[118:121], v70 offset:16960
	s_waitcnt lgkmcnt(1)
	v_mfma_f32_16x16x32_bf16 v[50:53], v[92:95], v[84:87], v[50:53]
	v_mfma_f32_16x16x32_bf16 v[42:45], v[96:99], v[84:87], v[42:45]
	ds_read_b128 v[84:87], v70 offset:25344
	ds_read_b128 v[122:125], v70 offset:25408
	s_waitcnt lgkmcnt(1)
	v_mfma_f32_16x16x32_bf16 v[38:41], v[92:95], v[84:87], v[38:41]
	v_mfma_f32_16x16x32_bf16 v[26:29], v[96:99], v[84:87], v[26:29]
	ds_read_b128 v[84:87], v70 offset:33792
	ds_read_b128 v[126:129], v70 offset:33856
	s_waitcnt lgkmcnt(1)
	v_mfma_f32_16x16x32_bf16 v[30:33], v[92:95], v[84:87], v[30:33]
	v_mfma_f32_16x16x32_bf16 v[34:37], v[96:99], v[84:87], v[34:37]
	ds_read_b128 v[84:87], v70 offset:42240
	ds_read_b128 v[130:133], v70 offset:42304
	s_waitcnt lgkmcnt(1)
	v_mfma_f32_16x16x32_bf16 v[18:21], v[92:95], v[84:87], v[18:21]
	v_mfma_f32_16x16x32_bf16 v[22:25], v[96:99], v[84:87], v[22:25]
	ds_read_b128 v[84:87], v70 offset:50688
	ds_read_b128 v[134:137], v70 offset:50752
	s_waitcnt lgkmcnt(1)
	v_mfma_f32_16x16x32_bf16 v[6:9], v[92:95], v[84:87], v[6:9]
	v_mfma_f32_16x16x32_bf16 v[10:13], v[96:99], v[84:87], v[10:13]
	ds_read_b128 v[84:87], v70 offset:59136
	ds_read_b128 v[138:141], v70 offset:59200
	v_add_u32_e32 v70, 0x80, v70
	s_waitcnt lgkmcnt(1)
	v_mfma_f32_16x16x32_bf16 v[2:5], v[92:95], v[84:87], v[2:5]
	v_mfma_f32_16x16x32_bf16 v[14:17], v[96:99], v[84:87], v[14:17]
	v_mfma_f32_16x16x32_bf16 v[62:65], v[100:103], v[88:91], v[62:65]
	v_mfma_f32_16x16x32_bf16 v[58:61], v[110:113], v[88:91], v[58:61]
	v_mfma_f32_16x16x32_bf16 v[54:57], v[100:103], v[114:117], v[54:57]
	v_mfma_f32_16x16x32_bf16 v[46:49], v[110:113], v[114:117], v[46:49]
	v_mfma_f32_16x16x32_bf16 v[50:53], v[100:103], v[118:121], v[50:53]
	v_mfma_f32_16x16x32_bf16 v[42:45], v[110:113], v[118:121], v[42:45]
	v_mfma_f32_16x16x32_bf16 v[38:41], v[100:103], v[122:125], v[38:41]
	v_mfma_f32_16x16x32_bf16 v[26:29], v[110:113], v[122:125], v[26:29]
	v_mfma_f32_16x16x32_bf16 v[30:33], v[100:103], v[126:129], v[30:33]
	v_mfma_f32_16x16x32_bf16 v[34:37], v[110:113], v[126:129], v[34:37]
	v_mfma_f32_16x16x32_bf16 v[18:21], v[100:103], v[130:133], v[18:21]
	v_mfma_f32_16x16x32_bf16 v[22:25], v[110:113], v[130:133], v[22:25]
	v_mfma_f32_16x16x32_bf16 v[6:9], v[100:103], v[134:137], v[6:9]
	v_mfma_f32_16x16x32_bf16 v[10:13], v[110:113], v[134:137], v[10:13]
	s_waitcnt lgkmcnt(0)
	v_mfma_f32_16x16x32_bf16 v[2:5], v[100:103], v[138:141], v[2:5]
	v_mfma_f32_16x16x32_bf16 v[14:17], v[110:113], v[138:141], v[14:17]
	v_lshl_add_u64 v[72:73], v[68:69], 0, s[4:5]
	v_add_co_u32_e32 v72, vcc, s23, v72
	v_lshl_add_u64 v[92:93], v[66:67], 0, s[4:5]
	s_nop 0
	v_addc_co_u32_e32 v73, vcc, 0, v73, vcc
	v_add_co_u32_e32 v110, vcc, s23, v92
	ds_read_b128 v[84:87], v70
	ds_read_b128 v[88:91], v70 offset:64
	v_addc_co_u32_e32 v111, vcc, 0, v93, vcc
	v_mov_b32_e32 v92, v216
	v_mov_b32_e32 v93, v217
	v_mov_b32_e32 v94, v218
	v_mov_b32_e32 v95, v219
	v_mov_b32_e32 v96, v220
	v_mov_b32_e32 v97, v221
	v_mov_b32_e32 v98, v222
	v_mov_b32_e32 v99, v223
	v_mov_b32_e32 v100, v224
	v_mov_b32_e32 v101, v225
	v_mov_b32_e32 v102, v226
	v_mov_b32_e32 v103, v227
	s_add_u32 s4, s4, 0x80
	v_mov_b32_e32 v110, v228
	v_mov_b32_e32 v111, v229
	v_mov_b32_e32 v112, v230
	v_mov_b32_e32 v113, v231
	s_addc_u32 s5, s5, 0
	s_cmpk_lg_i32 s4, 0x200
	s_waitcnt lgkmcnt(1)
	v_mfma_f32_16x16x32_bf16 v[62:65], v[92:95], v[84:87], v[62:65]
	v_mfma_f32_16x16x32_bf16 v[58:61], v[96:99], v[84:87], v[58:61]
	ds_read_b128 v[84:87], v70 offset:8448
	ds_read_b128 v[114:117], v70 offset:8512
	s_waitcnt lgkmcnt(1)
	v_mfma_f32_16x16x32_bf16 v[54:57], v[92:95], v[84:87], v[54:57]
	v_mfma_f32_16x16x32_bf16 v[46:49], v[96:99], v[84:87], v[46:49]
	ds_read_b128 v[84:87], v70 offset:16896
	ds_read_b128 v[118:121], v70 offset:16960
	s_waitcnt lgkmcnt(1)
	v_mfma_f32_16x16x32_bf16 v[50:53], v[92:95], v[84:87], v[50:53]
	v_mfma_f32_16x16x32_bf16 v[42:45], v[96:99], v[84:87], v[42:45]
	ds_read_b128 v[84:87], v70 offset:25344
	ds_read_b128 v[122:125], v70 offset:25408
	s_waitcnt lgkmcnt(1)
	v_mfma_f32_16x16x32_bf16 v[38:41], v[92:95], v[84:87], v[38:41]
	v_mfma_f32_16x16x32_bf16 v[26:29], v[96:99], v[84:87], v[26:29]
	ds_read_b128 v[84:87], v70 offset:33792
	ds_read_b128 v[126:129], v70 offset:33856
	s_waitcnt lgkmcnt(1)
	v_mfma_f32_16x16x32_bf16 v[30:33], v[92:95], v[84:87], v[30:33]
	v_mfma_f32_16x16x32_bf16 v[34:37], v[96:99], v[84:87], v[34:37]
	ds_read_b128 v[84:87], v70 offset:42240
	ds_read_b128 v[130:133], v70 offset:42304
	s_waitcnt lgkmcnt(1)
	v_mfma_f32_16x16x32_bf16 v[18:21], v[92:95], v[84:87], v[18:21]
	v_mfma_f32_16x16x32_bf16 v[22:25], v[96:99], v[84:87], v[22:25]
	ds_read_b128 v[84:87], v70 offset:50688
	ds_read_b128 v[134:137], v70 offset:50752
	s_waitcnt lgkmcnt(1)
	v_mfma_f32_16x16x32_bf16 v[6:9], v[92:95], v[84:87], v[6:9]
	v_mfma_f32_16x16x32_bf16 v[10:13], v[96:99], v[84:87], v[10:13]
	ds_read_b128 v[84:87], v70 offset:59136
	ds_read_b128 v[138:141], v70 offset:59200
	v_add_u32_e32 v70, 0x80, v70
	s_waitcnt lgkmcnt(1)
	v_mfma_f32_16x16x32_bf16 v[2:5], v[92:95], v[84:87], v[2:5]
	v_mfma_f32_16x16x32_bf16 v[14:17], v[96:99], v[84:87], v[14:17]
	v_mfma_f32_16x16x32_bf16 v[62:65], v[100:103], v[88:91], v[62:65]
	v_mfma_f32_16x16x32_bf16 v[58:61], v[110:113], v[88:91], v[58:61]
	v_mfma_f32_16x16x32_bf16 v[54:57], v[100:103], v[114:117], v[54:57]
	v_mfma_f32_16x16x32_bf16 v[46:49], v[110:113], v[114:117], v[46:49]
	v_mfma_f32_16x16x32_bf16 v[50:53], v[100:103], v[118:121], v[50:53]
	v_mfma_f32_16x16x32_bf16 v[42:45], v[110:113], v[118:121], v[42:45]
	v_mfma_f32_16x16x32_bf16 v[38:41], v[100:103], v[122:125], v[38:41]
	v_mfma_f32_16x16x32_bf16 v[26:29], v[110:113], v[122:125], v[26:29]
	v_mfma_f32_16x16x32_bf16 v[30:33], v[100:103], v[126:129], v[30:33]
	v_mfma_f32_16x16x32_bf16 v[34:37], v[110:113], v[126:129], v[34:37]
	v_mfma_f32_16x16x32_bf16 v[18:21], v[100:103], v[130:133], v[18:21]
	v_mfma_f32_16x16x32_bf16 v[22:25], v[110:113], v[130:133], v[22:25]
	v_mfma_f32_16x16x32_bf16 v[6:9], v[100:103], v[134:137], v[6:9]
	v_mfma_f32_16x16x32_bf16 v[10:13], v[110:113], v[134:137], v[10:13]
	s_waitcnt lgkmcnt(0)
	v_mfma_f32_16x16x32_bf16 v[2:5], v[100:103], v[138:141], v[2:5]
	v_mfma_f32_16x16x32_bf16 v[14:17], v[110:113], v[138:141], v[14:17]
	s_and_b32 s2, s28, 0xffffff80
	s_add_i32 s29, s29, s14
	v_or_b32_e32 v90, s2, v75
	v_readlane_b32 s36, v249, 0
	v_or_b32_e32 v76, s29, v105
	v_mov_b64_e32 v[70:71], s[0:1]
	v_readlane_b32 s46, v249, 10
	v_readlane_b32 s47, v249, 11
	v_or_b32_e32 v86, 32, v90
	v_mad_i64_i32 v[86:87], s[4:5], v86, s19, v[70:71]
	v_lshl_add_u64 v[110:111], v[76:77], 2, s[46:47]
	v_lshlrev_b32_e32 v76, 1, v76
	v_lshl_add_u64 v[88:89], v[86:87], 0, v[76:77]
	v_or_b32_e32 v86, 48, v90
	v_mad_i64_i32 v[86:87], s[4:5], v86, s19, v[70:71]
	v_lshl_add_u64 v[92:93], v[86:87], 0, v[76:77]
	v_or_b32_e32 v86, 64, v90
	v_mad_i64_i32 v[86:87], s[4:5], v86, s19, v[70:71]
	v_lshl_add_u64 v[98:99], v[86:87], 0, v[76:77]
	v_or_b32_e32 v86, 0x50, v90
	v_mad_i64_i32 v[72:73], s[4:5], v90, s19, v[70:71]
	v_or_b32_e32 v84, 16, v90
	v_mad_i64_i32 v[86:87], s[4:5], v86, s19, v[70:71]
	v_lshl_add_u64 v[72:73], v[72:73], 0, v[76:77]
	v_mad_i64_i32 v[84:85], s[4:5], v84, s19, v[70:71]
	v_lshl_add_u64 v[118:119], v[86:87], 0, v[76:77]
	v_or_b32_e32 v86, 0x60, v90
	global_load_dwordx4 v[66:69], v[110:111], off
	v_lshl_add_u64 v[84:85], v[84:85], 0, v[76:77]
	global_load_dwordx2 v[112:113], v[72:73], off offset:2048
	global_load_dwordx2 v[114:115], v[84:85], off offset:2048
	v_mad_i64_i32 v[86:87], s[4:5], v86, s19, v[70:71]
	v_lshl_add_u64 v[120:121], v[86:87], 0, v[76:77]
	v_or_b32_e32 v86, 0x70, v90
	v_mad_i64_i32 v[70:71], s[4:5], v86, s19, v[70:71]
	v_lshl_add_u64 v[70:71], v[70:71], 0, v[76:77]
	global_load_dwordx2 v[116:117], v[88:89], off offset:2048
	global_load_dwordx2 v[100:101], v[92:93], off offset:2048
	global_load_dwordx2 v[96:97], v[98:99], off offset:2048
	global_load_dwordx2 v[94:95], v[118:119], off offset:2048
	global_load_dwordx2 v[90:91], v[120:121], off offset:2048
	global_load_dwordx2 v[86:87], v[70:71], off offset:2048
	global_load_dwordx2 v[122:123], v[84:85], off offset:2080
	global_load_dwordx2 v[124:125], v[72:73], off offset:2080
	global_load_dwordx2 v[102:103], v[92:93], off offset:2080
	global_load_dwordx2 v[126:127], v[88:89], off offset:2080
	s_nop 0
	global_load_dwordx2 v[92:93], v[118:119], off offset:2080
	s_nop 0
	global_load_dwordx2 v[98:99], v[98:99], off offset:2080
	s_nop 0
	global_load_dwordx2 v[84:85], v[70:71], off offset:2080
	global_load_dwordx2 v[88:89], v[120:121], off offset:2080
	s_nop 0
	global_load_dwordx4 v[70:73], v[110:111], off offset:64
	s_ashr_i32 s4, s27, 2
	s_ashr_i32 s5, s4, 31
	s_lshl_b64 s[4:5], s[4:5], 20
	s_add_u32 s6, s15, s4
	v_lshlrev_b32_e32 v110, 2, v75
	s_addc_u32 s7, s16, s5
	s_lshr_b32 s2, s29, 6
	v_and_b32_e32 v119, 32, v110
	s_lshl_b64 s[4:5], s[2:3], 14
	s_lshl_b32 s2, s29, 5
	s_and_b32 s2, s2, 0x400
	v_lshlrev_b32_e32 v118, 6, v75
	s_add_u32 s4, s6, s4
	s_addc_u32 s5, s7, s5
	s_add_i32 s17, s17, s18
	v_readlane_b32 s37, v249, 1
	v_readlane_b32 s38, v249, 2
	v_readlane_b32 s39, v249, 3
	v_readlane_b32 s40, v249, 4
	v_readlane_b32 s41, v249, 5
	v_readlane_b32 s42, v249, 6
	v_readlane_b32 s43, v249, 7
	v_readlane_b32 s44, v249, 8
	v_readlane_b32 s45, v249, 9
	v_readlane_b32 s48, v249, 12
	v_readlane_b32 s49, v249, 13
	v_readlane_b32 s50, v249, 14
	v_readlane_b32 s51, v249, 15
	s_waitcnt vmcnt(16)
	v_pk_mul_f32 v[64:65], v[64:65], v[68:69]
	v_pk_mul_f32 v[62:63], v[62:63], v[66:67]
	v_lshlrev_b32_e32 v110, 16, v112
	v_and_b32_e32 v111, 0xffff0000, v112
	v_lshlrev_b32_e32 v112, 16, v113
	v_and_b32_e32 v113, 0xffff0000, v113
	v_pk_mul_f32 v[62:63], v[62:63], v[110:111]
	v_pk_mul_f32 v[64:65], v[64:65], v[112:113]
	v_cvt_pk_bf16_f32 v62, v62, v63
	v_cvt_pk_bf16_f32 v63, v64, v65
	v_and_or_b32 v64, v76, 24, s2
	v_or3_b32 v64, v64, v118, v119
	s_waitcnt vmcnt(15)
	s_waitcnt vmcnt(14)
	s_waitcnt vmcnt(13)
	s_waitcnt vmcnt(12)
	s_waitcnt vmcnt(11)
	s_waitcnt vmcnt(10)
	s_waitcnt vmcnt(9)
	s_waitcnt vmcnt(7)
	s_waitcnt vmcnt(5)
	s_waitcnt vmcnt(3)
	s_waitcnt vmcnt(1)
	global_store_dwordx2 v64, v[62:63], s[4:5]
	v_lshlrev_b32_e32 v62, 16, v124
	v_and_b32_e32 v63, 0xffff0000, v124
	s_waitcnt vmcnt(1)
	v_pk_mul_f32 v[58:59], v[58:59], v[70:71]
	v_pk_mul_f32 v[60:61], v[60:61], v[72:73]
	v_pk_mul_f32 v[58:59], v[58:59], v[62:63]
	v_lshlrev_b32_e32 v62, 16, v125
	v_and_b32_e32 v63, 0xffff0000, v125
	v_pk_mul_f32 v[60:61], v[60:61], v[62:63]
	v_cvt_pk_bf16_f32 v58, v58, v59
	v_cvt_pk_bf16_f32 v59, v60, v61
	v_bitop3_b32 v60, v76, 56, 32 bitop3:0xc8
	v_bitop3_b32 v60, v60, v119, v118 bitop3:0x36
	v_or_b32_e32 v76, s2, v60
	global_store_dwordx2 v76, v[58:59], s[4:5]
	v_lshlrev_b32_e32 v58, 16, v114
	v_and_b32_e32 v59, 0xffff0000, v114
	v_pk_mul_f32 v[54:55], v[54:55], v[66:67]
	v_pk_mul_f32 v[56:57], v[56:57], v[68:69]
	v_pk_mul_f32 v[54:55], v[54:55], v[58:59]
	v_lshlrev_b32_e32 v58, 16, v115
	v_and_b32_e32 v59, 0xffff0000, v115
	v_pk_mul_f32 v[56:57], v[56:57], v[58:59]
	v_cvt_pk_bf16_f32 v54, v54, v55
	v_cvt_pk_bf16_f32 v55, v56, v57
	global_store_dwordx2 v64, v[54:55], s[4:5] offset:2048
	v_lshlrev_b32_e32 v54, 16, v122
	v_and_b32_e32 v55, 0xffff0000, v122
	v_pk_mul_f32 v[46:47], v[46:47], v[70:71]
	v_pk_mul_f32 v[48:49], v[48:49], v[72:73]
	v_pk_mul_f32 v[46:47], v[46:47], v[54:55]
	v_lshlrev_b32_e32 v54, 16, v123
	v_and_b32_e32 v55, 0xffff0000, v123
	v_pk_mul_f32 v[48:49], v[48:49], v[54:55]
	v_cvt_pk_bf16_f32 v46, v46, v47
	v_cvt_pk_bf16_f32 v47, v48, v49
	global_store_dwordx2 v76, v[46:47], s[4:5] offset:2048
	v_lshlrev_b32_e32 v46, 16, v116
	v_and_b32_e32 v47, 0xffff0000, v116
	v_pk_mul_f32 v[50:51], v[50:51], v[66:67]
	v_mov_b32_e32 v65, v77
	v_pk_mul_f32 v[48:49], v[52:53], v[68:69]
	v_pk_mul_f32 v[46:47], v[50:51], v[46:47]
	v_lshlrev_b32_e32 v50, 16, v117
	v_and_b32_e32 v51, 0xffff0000, v117
	v_lshl_add_u64 v[110:111], s[4:5], 0, v[64:65]
	v_pk_mul_f32 v[48:49], v[48:49], v[50:51]
	v_cvt_pk_bf16_f32 v46, v46, v47
	v_cvt_pk_bf16_f32 v47, v48, v49
	v_add_co_u32_e32 v48, vcc, s24, v110
	v_pk_mul_f32 v[42:43], v[42:43], v[70:71]
	s_nop 0
	v_addc_co_u32_e32 v49, vcc, 0, v111, vcc
	v_add_co_u32_e32 v50, vcc, s20, v110
	v_pk_mul_f32 v[44:45], v[44:45], v[72:73]
	s_nop 0
	v_addc_co_u32_e32 v51, vcc, 0, v111, vcc
	global_store_dwordx2 v[50:51], v[46:47], off offset:-4096
	v_lshlrev_b32_e32 v46, 16, v126
	v_and_b32_e32 v47, 0xffff0000, v126
	v_pk_mul_f32 v[42:43], v[42:43], v[46:47]
	v_lshlrev_b32_e32 v46, 16, v127
	v_and_b32_e32 v47, 0xffff0000, v127
	v_lshl_add_u64 v[60:61], s[4:5], 0, v[76:77]
	v_pk_mul_f32 v[44:45], v[44:45], v[46:47]
	v_cvt_pk_bf16_f32 v42, v42, v43
	v_cvt_pk_bf16_f32 v43, v44, v45
	v_add_co_u32_e32 v44, vcc, s24, v60
	v_pk_mul_f32 v[38:39], v[38:39], v[66:67]
	s_nop 0
	v_addc_co_u32_e32 v45, vcc, 0, v61, vcc
	v_add_co_u32_e32 v46, vcc, s20, v60
	v_pk_mul_f32 v[40:41], v[40:41], v[68:69]
	s_nop 0
	v_addc_co_u32_e32 v47, vcc, 0, v61, vcc
	global_store_dwordx2 v[46:47], v[42:43], off offset:-4096
	v_lshlrev_b32_e32 v42, 16, v100
	v_and_b32_e32 v43, 0xffff0000, v100
	v_pk_mul_f32 v[38:39], v[38:39], v[42:43]
	v_lshlrev_b32_e32 v42, 16, v101
	v_and_b32_e32 v43, 0xffff0000, v101
	v_pk_mul_f32 v[40:41], v[40:41], v[42:43]
	v_cvt_pk_bf16_f32 v38, v38, v39
	v_cvt_pk_bf16_f32 v39, v40, v41
	global_store_dwordx2 v[48:49], v[38:39], off offset:2048
	v_lshlrev_b32_e32 v38, 16, v102
	v_and_b32_e32 v39, 0xffff0000, v102
	v_pk_mul_f32 v[26:27], v[26:27], v[70:71]
	v_pk_mul_f32 v[28:29], v[28:29], v[72:73]
	v_pk_mul_f32 v[26:27], v[26:27], v[38:39]
	v_lshlrev_b32_e32 v38, 16, v103
	v_and_b32_e32 v39, 0xffff0000, v103
	v_pk_mul_f32 v[28:29], v[28:29], v[38:39]
	v_cvt_pk_bf16_f32 v26, v26, v27
	v_cvt_pk_bf16_f32 v27, v28, v29
	global_store_dwordx2 v[44:45], v[26:27], off offset:2048
	v_lshlrev_b32_e32 v26, 16, v96
	v_and_b32_e32 v27, 0xffff0000, v96
	v_pk_mul_f32 v[30:31], v[30:31], v[66:67]
	v_pk_mul_f32 v[28:29], v[32:33], v[68:69]
	v_pk_mul_f32 v[26:27], v[30:31], v[26:27]
	v_lshlrev_b32_e32 v30, 16, v97
	v_and_b32_e32 v31, 0xffff0000, v97
	v_pk_mul_f32 v[28:29], v[28:29], v[30:31]
	v_cvt_pk_bf16_f32 v26, v26, v27
	v_cvt_pk_bf16_f32 v27, v28, v29
	global_store_dwordx2 v[50:51], v[26:27], off
	v_lshlrev_b32_e32 v26, 16, v98
	v_and_b32_e32 v27, 0xffff0000, v98
	v_pk_mul_f32 v[30:31], v[34:35], v[70:71]
	v_pk_mul_f32 v[28:29], v[36:37], v[72:73]
	v_pk_mul_f32 v[26:27], v[30:31], v[26:27]
	v_lshlrev_b32_e32 v30, 16, v99
	v_and_b32_e32 v31, 0xffff0000, v99
	v_pk_mul_f32 v[28:29], v[28:29], v[30:31]
	v_cvt_pk_bf16_f32 v26, v26, v27
	v_cvt_pk_bf16_f32 v27, v28, v29
	global_store_dwordx2 v[46:47], v[26:27], off
	v_lshlrev_b32_e32 v26, 16, v94
	v_and_b32_e32 v27, 0xffff0000, v94
	v_pk_mul_f32 v[18:19], v[18:19], v[66:67]
	v_pk_mul_f32 v[20:21], v[20:21], v[68:69]
	v_pk_mul_f32 v[18:19], v[18:19], v[26:27]
	v_lshlrev_b32_e32 v26, 16, v95
	v_and_b32_e32 v27, 0xffff0000, v95
	v_pk_mul_f32 v[20:21], v[20:21], v[26:27]
	v_cvt_pk_bf16_f32 v18, v18, v19
	v_cvt_pk_bf16_f32 v19, v20, v21
	global_store_dwordx2 v[50:51], v[18:19], off offset:2048
	v_lshlrev_b32_e32 v18, 16, v92
	v_and_b32_e32 v19, 0xffff0000, v92
	v_pk_mul_f32 v[22:23], v[22:23], v[70:71]
	v_pk_mul_f32 v[20:21], v[24:25], v[72:73]
	v_pk_mul_f32 v[18:19], v[22:23], v[18:19]
	v_lshlrev_b32_e32 v22, 16, v93
	v_and_b32_e32 v23, 0xffff0000, v93
	v_pk_mul_f32 v[20:21], v[20:21], v[22:23]
	v_cvt_pk_bf16_f32 v18, v18, v19
	v_cvt_pk_bf16_f32 v19, v20, v21
	global_store_dwordx2 v[46:47], v[18:19], off offset:2048
	v_lshlrev_b32_e32 v18, 16, v90
	v_and_b32_e32 v19, 0xffff0000, v90
	v_pk_mul_f32 v[6:7], v[6:7], v[66:67]
	v_pk_mul_f32 v[8:9], v[8:9], v[68:69]
	v_pk_mul_f32 v[6:7], v[6:7], v[18:19]
	v_lshlrev_b32_e32 v18, 16, v91
	v_and_b32_e32 v19, 0xffff0000, v91
	v_pk_mul_f32 v[8:9], v[8:9], v[18:19]
	v_cvt_pk_bf16_f32 v6, v6, v7
	v_cvt_pk_bf16_f32 v7, v8, v9
	v_add_co_u32_e32 v8, vcc, s25, v110
	v_pk_mul_f32 v[10:11], v[10:11], v[70:71]
	s_nop 0
	v_addc_co_u32_e32 v9, vcc, 0, v111, vcc
	global_store_dwordx2 v[8:9], v[6:7], off
	v_lshlrev_b32_e32 v6, 16, v88
	v_and_b32_e32 v7, 0xffff0000, v88
	v_pk_mul_f32 v[12:13], v[12:13], v[72:73]
	v_pk_mul_f32 v[6:7], v[10:11], v[6:7]
	v_lshlrev_b32_e32 v10, 16, v89
	v_and_b32_e32 v11, 0xffff0000, v89
	v_pk_mul_f32 v[10:11], v[12:13], v[10:11]
	v_cvt_pk_bf16_f32 v6, v6, v7
	v_cvt_pk_bf16_f32 v7, v10, v11
	v_add_co_u32_e32 v10, vcc, s25, v60
	v_pk_mul_f32 v[2:3], v[2:3], v[66:67]
	s_nop 0
	v_addc_co_u32_e32 v11, vcc, 0, v61, vcc
	global_store_dwordx2 v[10:11], v[6:7], off
	v_lshlrev_b32_e32 v6, 16, v86
	v_and_b32_e32 v7, 0xffff0000, v86
	v_pk_mul_f32 v[4:5], v[4:5], v[68:69]
	v_pk_mul_f32 v[2:3], v[2:3], v[6:7]
	v_lshlrev_b32_e32 v6, 16, v87
	v_and_b32_e32 v7, 0xffff0000, v87
	v_pk_mul_f32 v[4:5], v[4:5], v[6:7]
	v_cvt_pk_bf16_f32 v2, v2, v3
	v_cvt_pk_bf16_f32 v3, v4, v5
	global_store_dwordx2 v[8:9], v[2:3], off offset:2048
	v_lshlrev_b32_e32 v2, 16, v84
	v_and_b32_e32 v3, 0xffff0000, v84
	v_pk_mul_f32 v[6:7], v[14:15], v[70:71]
	v_pk_mul_f32 v[4:5], v[16:17], v[72:73]
	v_pk_mul_f32 v[2:3], v[6:7], v[2:3]
	v_lshlrev_b32_e32 v6, 16, v85
	v_and_b32_e32 v7, 0xffff0000, v85
	v_readlane_b32 s4, v249, 34
	v_pk_mul_f32 v[4:5], v[4:5], v[6:7]
	s_add_i32 s27, s27, s4
	s_add_i32 s26, s26, s4
	v_cvt_pk_bf16_f32 v2, v2, v3
	v_cvt_pk_bf16_f32 v3, v4, v5
	s_cmpk_gt_i32 s27, 0xff
	v_readlane_b32 s5, v249, 35
	global_store_dwordx2 v[10:11], v[2:3], off offset:2048
	s_cbranch_scc0 .LBB0_585

.LBB0_1402:
	s_or_b64 exec, exec, s[10:11]
	s_and_b32 s2, s28, 3
	s_lshl_b32 s2, s2, 17
	v_mov_b32_e32 v26, 0
	v_lshl_add_u64 v[66:67], v[80:81], 0, s[2:3]
	v_lshl_add_u64 v[68:69], v[82:83], 0, s[2:3]
	s_mov_b64 s[4:5], 0
	v_mov_b32_e32 v70, v105
	v_mov_b32_e32 v27, v26
	v_mov_b32_e32 v28, v26
	v_mov_b32_e32 v29, v26
	v_mov_b32_e32 v42, v26
	v_mov_b32_e32 v43, v26
	v_mov_b32_e32 v44, v26
	v_mov_b32_e32 v45, v26
	v_mov_b32_e32 v46, v26
	v_mov_b32_e32 v47, v26
	v_mov_b32_e32 v48, v26
	v_mov_b32_e32 v49, v26
	v_mov_b32_e32 v58, v26
	v_mov_b32_e32 v59, v26
	v_mov_b32_e32 v60, v26
	v_mov_b32_e32 v61, v26
	v_mov_b32_e32 v2, v26
	v_mov_b32_e32 v3, v26
	v_mov_b32_e32 v4, v26
	v_mov_b32_e32 v5, v26
	v_mov_b32_e32 v6, v26
	v_mov_b32_e32 v7, v26
	v_mov_b32_e32 v8, v26
	v_mov_b32_e32 v9, v26
	v_mov_b32_e32 v18, v26
	v_mov_b32_e32 v19, v26
	v_mov_b32_e32 v20, v26
	v_mov_b32_e32 v21, v26
	v_mov_b32_e32 v30, v26
	v_mov_b32_e32 v31, v26
	v_mov_b32_e32 v32, v26
	v_mov_b32_e32 v33, v26
	v_mov_b32_e32 v38, v26
	v_mov_b32_e32 v39, v26
	v_mov_b32_e32 v40, v26
	v_mov_b32_e32 v41, v26
	v_mov_b32_e32 v50, v26
	v_mov_b32_e32 v51, v26
	v_mov_b32_e32 v52, v26
	v_mov_b32_e32 v53, v26
	v_mov_b32_e32 v54, v26
	v_mov_b32_e32 v55, v26
	v_mov_b32_e32 v56, v26
	v_mov_b32_e32 v57, v26
	v_mov_b32_e32 v62, v26
	v_mov_b32_e32 v63, v26
	v_mov_b32_e32 v64, v26
	v_mov_b32_e32 v65, v26
	v_mov_b32_e32 v34, v26
	v_mov_b32_e32 v35, v26
	v_mov_b32_e32 v36, v26
	v_mov_b32_e32 v37, v26
	v_mov_b32_e32 v22, v26
	v_mov_b32_e32 v23, v26
	v_mov_b32_e32 v24, v26
	v_mov_b32_e32 v25, v26
	v_mov_b32_e32 v10, v26
	v_mov_b32_e32 v11, v26
	v_mov_b32_e32 v12, v26
	v_mov_b32_e32 v13, v26
	v_mov_b32_e32 v14, v26
	v_mov_b32_e32 v15, v26
	v_mov_b32_e32 v16, v26
	v_mov_b32_e32 v17, v26
	v_add_co_u32_e32 v232, vcc, s25, v68
	s_nop 1
	v_addc_co_u32_e32 v233, vcc, 0, v69, vcc
	v_add_co_u32_e32 v234, vcc, s25, v66
	s_nop 1
	v_addc_co_u32_e32 v235, vcc, 0, v67, vcc
	global_load_dwordx4 v[144:147], v[232:233], off
	global_load_dwordx4 v[148:151], v[234:235], off
	global_load_dwordx4 v[152:155], v[232:233], off offset:64
	global_load_dwordx4 v[156:159], v[234:235], off offset:64
	global_load_dwordx4 v[160:163], v[232:233], off offset:128
	global_load_dwordx4 v[164:167], v[234:235], off offset:128
	global_load_dwordx4 v[168:171], v[232:233], off offset:192
	global_load_dwordx4 v[172:175], v[234:235], off offset:192
	global_load_dwordx4 v[200:203], v[232:233], off offset:256
	global_load_dwordx4 v[204:207], v[234:235], off offset:256
	global_load_dwordx4 v[208:211], v[232:233], off offset:320
	global_load_dwordx4 v[212:215], v[234:235], off offset:320
	global_load_dwordx4 v[216:219], v[232:233], off offset:384
	global_load_dwordx4 v[220:223], v[234:235], off offset:384
	global_load_dwordx4 v[224:227], v[232:233], off offset:448
	global_load_dwordx4 v[228:231], v[234:235], off offset:448
	s_waitcnt lgkmcnt(0)
	s_barrier
.LBB0_1403:
	s_waitcnt vmcnt(0)
	v_lshl_add_u64 v[72:73], v[68:69], 0, s[4:5]
	v_add_co_u32_e32 v72, vcc, s25, v72
	v_lshl_add_u64 v[92:93], v[66:67], 0, s[4:5]
	s_nop 0
	v_addc_co_u32_e32 v73, vcc, 0, v73, vcc
	v_add_co_u32_e32 v112, vcc, s25, v92
	ds_read_b128 v[84:87], v70
	ds_read_b128 v[88:91], v70 offset:64
	v_addc_co_u32_e32 v113, vcc, 0, v93, vcc
	v_mov_b32_e32 v92, v144
	v_mov_b32_e32 v93, v145
	v_mov_b32_e32 v94, v146
	v_mov_b32_e32 v95, v147
	v_mov_b32_e32 v96, v148
	v_mov_b32_e32 v97, v149
	v_mov_b32_e32 v98, v150
	v_mov_b32_e32 v99, v151
	v_mov_b32_e32 v100, v152
	v_mov_b32_e32 v101, v153
	v_mov_b32_e32 v102, v154
	v_mov_b32_e32 v103, v155
	s_add_u32 s4, s4, 0x80
	v_mov_b32_e32 v112, v156
	v_mov_b32_e32 v113, v157
	v_mov_b32_e32 v114, v158
	v_mov_b32_e32 v115, v159
	s_addc_u32 s5, s5, 0
	s_cmpk_lg_i32 s4, 0x200
	s_waitcnt lgkmcnt(1)
	v_mfma_f32_16x16x32_bf16 v[62:65], v[92:95], v[84:87], v[62:65]
	v_mfma_f32_16x16x32_bf16 v[58:61], v[96:99], v[84:87], v[58:61]
	ds_read_b128 v[84:87], v70 offset:8448
	ds_read_b128 v[116:119], v70 offset:8512
	s_waitcnt lgkmcnt(1)
	v_mfma_f32_16x16x32_bf16 v[54:57], v[92:95], v[84:87], v[54:57]
	v_mfma_f32_16x16x32_bf16 v[46:49], v[96:99], v[84:87], v[46:49]
	ds_read_b128 v[84:87], v70 offset:16896
	ds_read_b128 v[120:123], v70 offset:16960
	s_waitcnt lgkmcnt(1)
	v_mfma_f32_16x16x32_bf16 v[50:53], v[92:95], v[84:87], v[50:53]
	v_mfma_f32_16x16x32_bf16 v[42:45], v[96:99], v[84:87], v[42:45]
	ds_read_b128 v[84:87], v70 offset:25344
	ds_read_b128 v[124:127], v70 offset:25408
	s_waitcnt lgkmcnt(1)
	v_mfma_f32_16x16x32_bf16 v[38:41], v[92:95], v[84:87], v[38:41]
	v_mfma_f32_16x16x32_bf16 v[26:29], v[96:99], v[84:87], v[26:29]
	ds_read_b128 v[84:87], v70 offset:33792
	ds_read_b128 v[128:131], v70 offset:33856
	s_waitcnt lgkmcnt(1)
	v_mfma_f32_16x16x32_bf16 v[30:33], v[92:95], v[84:87], v[30:33]
	v_mfma_f32_16x16x32_bf16 v[34:37], v[96:99], v[84:87], v[34:37]
	ds_read_b128 v[84:87], v70 offset:42240
	ds_read_b128 v[132:135], v70 offset:42304
	s_waitcnt lgkmcnt(1)
	v_mfma_f32_16x16x32_bf16 v[18:21], v[92:95], v[84:87], v[18:21]
	v_mfma_f32_16x16x32_bf16 v[22:25], v[96:99], v[84:87], v[22:25]
	ds_read_b128 v[84:87], v70 offset:50688
	ds_read_b128 v[136:139], v70 offset:50752
	s_waitcnt lgkmcnt(1)
	v_mfma_f32_16x16x32_bf16 v[6:9], v[92:95], v[84:87], v[6:9]
	v_mfma_f32_16x16x32_bf16 v[10:13], v[96:99], v[84:87], v[10:13]
	ds_read_b128 v[84:87], v70 offset:59136
	ds_read_b128 v[140:143], v70 offset:59200
	v_add_u32_e32 v70, 0x80, v70
	s_waitcnt lgkmcnt(1)
	v_mfma_f32_16x16x32_bf16 v[2:5], v[92:95], v[84:87], v[2:5]
	v_mfma_f32_16x16x32_bf16 v[14:17], v[96:99], v[84:87], v[14:17]
	v_mfma_f32_16x16x32_bf16 v[62:65], v[100:103], v[88:91], v[62:65]
	v_mfma_f32_16x16x32_bf16 v[58:61], v[112:115], v[88:91], v[58:61]
	v_mfma_f32_16x16x32_bf16 v[54:57], v[100:103], v[116:119], v[54:57]
	v_mfma_f32_16x16x32_bf16 v[46:49], v[112:115], v[116:119], v[46:49]
	v_mfma_f32_16x16x32_bf16 v[50:53], v[100:103], v[120:123], v[50:53]
	v_mfma_f32_16x16x32_bf16 v[42:45], v[112:115], v[120:123], v[42:45]
	v_mfma_f32_16x16x32_bf16 v[38:41], v[100:103], v[124:127], v[38:41]
	v_mfma_f32_16x16x32_bf16 v[26:29], v[112:115], v[124:127], v[26:29]
	v_mfma_f32_16x16x32_bf16 v[30:33], v[100:103], v[128:131], v[30:33]
	v_mfma_f32_16x16x32_bf16 v[34:37], v[112:115], v[128:131], v[34:37]
	v_mfma_f32_16x16x32_bf16 v[18:21], v[100:103], v[132:135], v[18:21]
	v_mfma_f32_16x16x32_bf16 v[22:25], v[112:115], v[132:135], v[22:25]
	v_mfma_f32_16x16x32_bf16 v[6:9], v[100:103], v[136:139], v[6:9]
	v_mfma_f32_16x16x32_bf16 v[10:13], v[112:115], v[136:139], v[10:13]
	s_waitcnt lgkmcnt(0)
	v_mfma_f32_16x16x32_bf16 v[2:5], v[100:103], v[140:143], v[2:5]
	v_mfma_f32_16x16x32_bf16 v[14:17], v[112:115], v[140:143], v[14:17]
	v_lshl_add_u64 v[72:73], v[68:69], 0, s[4:5]
	v_add_co_u32_e32 v72, vcc, s25, v72
	v_lshl_add_u64 v[92:93], v[66:67], 0, s[4:5]
	s_nop 0
	v_addc_co_u32_e32 v73, vcc, 0, v73, vcc
	v_add_co_u32_e32 v112, vcc, s25, v92
	ds_read_b128 v[84:87], v70
	ds_read_b128 v[88:91], v70 offset:64
	v_addc_co_u32_e32 v113, vcc, 0, v93, vcc
	v_mov_b32_e32 v92, v160
	v_mov_b32_e32 v93, v161
	v_mov_b32_e32 v94, v162
	v_mov_b32_e32 v95, v163
	v_mov_b32_e32 v96, v164
	v_mov_b32_e32 v97, v165
	v_mov_b32_e32 v98, v166
	v_mov_b32_e32 v99, v167
	v_mov_b32_e32 v100, v168
	v_mov_b32_e32 v101, v169
	v_mov_b32_e32 v102, v170
	v_mov_b32_e32 v103, v171
	s_add_u32 s4, s4, 0x80
	v_mov_b32_e32 v112, v172
	v_mov_b32_e32 v113, v173
	v_mov_b32_e32 v114, v174
	v_mov_b32_e32 v115, v175
	s_addc_u32 s5, s5, 0
	s_cmpk_lg_i32 s4, 0x200
	s_waitcnt lgkmcnt(1)
	v_mfma_f32_16x16x32_bf16 v[62:65], v[92:95], v[84:87], v[62:65]
	v_mfma_f32_16x16x32_bf16 v[58:61], v[96:99], v[84:87], v[58:61]
	ds_read_b128 v[84:87], v70 offset:8448
	ds_read_b128 v[116:119], v70 offset:8512
	s_waitcnt lgkmcnt(1)
	v_mfma_f32_16x16x32_bf16 v[54:57], v[92:95], v[84:87], v[54:57]
	v_mfma_f32_16x16x32_bf16 v[46:49], v[96:99], v[84:87], v[46:49]
	ds_read_b128 v[84:87], v70 offset:16896
	ds_read_b128 v[120:123], v70 offset:16960
	s_waitcnt lgkmcnt(1)
	v_mfma_f32_16x16x32_bf16 v[50:53], v[92:95], v[84:87], v[50:53]
	v_mfma_f32_16x16x32_bf16 v[42:45], v[96:99], v[84:87], v[42:45]
	ds_read_b128 v[84:87], v70 offset:25344
	ds_read_b128 v[124:127], v70 offset:25408
	s_waitcnt lgkmcnt(1)
	v_mfma_f32_16x16x32_bf16 v[38:41], v[92:95], v[84:87], v[38:41]
	v_mfma_f32_16x16x32_bf16 v[26:29], v[96:99], v[84:87], v[26:29]
	ds_read_b128 v[84:87], v70 offset:33792
	ds_read_b128 v[128:131], v70 offset:33856
	s_waitcnt lgkmcnt(1)
	v_mfma_f32_16x16x32_bf16 v[30:33], v[92:95], v[84:87], v[30:33]
	v_mfma_f32_16x16x32_bf16 v[34:37], v[96:99], v[84:87], v[34:37]
	ds_read_b128 v[84:87], v70 offset:42240
	ds_read_b128 v[132:135], v70 offset:42304
	s_waitcnt lgkmcnt(1)
	v_mfma_f32_16x16x32_bf16 v[18:21], v[92:95], v[84:87], v[18:21]
	v_mfma_f32_16x16x32_bf16 v[22:25], v[96:99], v[84:87], v[22:25]
	ds_read_b128 v[84:87], v70 offset:50688
	ds_read_b128 v[136:139], v70 offset:50752
	s_waitcnt lgkmcnt(1)
	v_mfma_f32_16x16x32_bf16 v[6:9], v[92:95], v[84:87], v[6:9]
	v_mfma_f32_16x16x32_bf16 v[10:13], v[96:99], v[84:87], v[10:13]
	ds_read_b128 v[84:87], v70 offset:59136
	ds_read_b128 v[140:143], v70 offset:59200
	v_add_u32_e32 v70, 0x80, v70
	s_waitcnt lgkmcnt(1)
	v_mfma_f32_16x16x32_bf16 v[2:5], v[92:95], v[84:87], v[2:5]
	v_mfma_f32_16x16x32_bf16 v[14:17], v[96:99], v[84:87], v[14:17]
	v_mfma_f32_16x16x32_bf16 v[62:65], v[100:103], v[88:91], v[62:65]
	v_mfma_f32_16x16x32_bf16 v[58:61], v[112:115], v[88:91], v[58:61]
	v_mfma_f32_16x16x32_bf16 v[54:57], v[100:103], v[116:119], v[54:57]
	v_mfma_f32_16x16x32_bf16 v[46:49], v[112:115], v[116:119], v[46:49]
	v_mfma_f32_16x16x32_bf16 v[50:53], v[100:103], v[120:123], v[50:53]
	v_mfma_f32_16x16x32_bf16 v[42:45], v[112:115], v[120:123], v[42:45]
	v_mfma_f32_16x16x32_bf16 v[38:41], v[100:103], v[124:127], v[38:41]
	v_mfma_f32_16x16x32_bf16 v[26:29], v[112:115], v[124:127], v[26:29]
	v_mfma_f32_16x16x32_bf16 v[30:33], v[100:103], v[128:131], v[30:33]
	v_mfma_f32_16x16x32_bf16 v[34:37], v[112:115], v[128:131], v[34:37]
	v_mfma_f32_16x16x32_bf16 v[18:21], v[100:103], v[132:135], v[18:21]
	v_mfma_f32_16x16x32_bf16 v[22:25], v[112:115], v[132:135], v[22:25]
	v_mfma_f32_16x16x32_bf16 v[6:9], v[100:103], v[136:139], v[6:9]
	v_mfma_f32_16x16x32_bf16 v[10:13], v[112:115], v[136:139], v[10:13]
	s_waitcnt lgkmcnt(0)
	v_mfma_f32_16x16x32_bf16 v[2:5], v[100:103], v[140:143], v[2:5]
	v_mfma_f32_16x16x32_bf16 v[14:17], v[112:115], v[140:143], v[14:17]
	v_lshl_add_u64 v[72:73], v[68:69], 0, s[4:5]
	v_add_co_u32_e32 v72, vcc, s25, v72
	v_lshl_add_u64 v[92:93], v[66:67], 0, s[4:5]
	s_nop 0
	v_addc_co_u32_e32 v73, vcc, 0, v73, vcc
	v_add_co_u32_e32 v112, vcc, s25, v92
	ds_read_b128 v[84:87], v70
	ds_read_b128 v[88:91], v70 offset:64
	v_addc_co_u32_e32 v113, vcc, 0, v93, vcc
	v_mov_b32_e32 v92, v200
	v_mov_b32_e32 v93, v201
	v_mov_b32_e32 v94, v202
	v_mov_b32_e32 v95, v203
	v_mov_b32_e32 v96, v204
	v_mov_b32_e32 v97, v205
	v_mov_b32_e32 v98, v206
	v_mov_b32_e32 v99, v207
	v_mov_b32_e32 v100, v208
	v_mov_b32_e32 v101, v209
	v_mov_b32_e32 v102, v210
	v_mov_b32_e32 v103, v211
	s_add_u32 s4, s4, 0x80
	v_mov_b32_e32 v112, v212
	v_mov_b32_e32 v113, v213
	v_mov_b32_e32 v114, v214
	v_mov_b32_e32 v115, v215
	s_addc_u32 s5, s5, 0
	s_cmpk_lg_i32 s4, 0x200
	s_waitcnt lgkmcnt(1)
	v_mfma_f32_16x16x32_bf16 v[62:65], v[92:95], v[84:87], v[62:65]
	v_mfma_f32_16x16x32_bf16 v[58:61], v[96:99], v[84:87], v[58:61]
	ds_read_b128 v[84:87], v70 offset:8448
	ds_read_b128 v[116:119], v70 offset:8512
	s_waitcnt lgkmcnt(1)
	v_mfma_f32_16x16x32_bf16 v[54:57], v[92:95], v[84:87], v[54:57]
	v_mfma_f32_16x16x32_bf16 v[46:49], v[96:99], v[84:87], v[46:49]
	ds_read_b128 v[84:87], v70 offset:16896
	ds_read_b128 v[120:123], v70 offset:16960
	s_waitcnt lgkmcnt(1)
	v_mfma_f32_16x16x32_bf16 v[50:53], v[92:95], v[84:87], v[50:53]
	v_mfma_f32_16x16x32_bf16 v[42:45], v[96:99], v[84:87], v[42:45]
	ds_read_b128 v[84:87], v70 offset:25344
	ds_read_b128 v[124:127], v70 offset:25408
	s_waitcnt lgkmcnt(1)
	v_mfma_f32_16x16x32_bf16 v[38:41], v[92:95], v[84:87], v[38:41]
	v_mfma_f32_16x16x32_bf16 v[26:29], v[96:99], v[84:87], v[26:29]
	ds_read_b128 v[84:87], v70 offset:33792
	ds_read_b128 v[128:131], v70 offset:33856
	s_waitcnt lgkmcnt(1)
	v_mfma_f32_16x16x32_bf16 v[30:33], v[92:95], v[84:87], v[30:33]
	v_mfma_f32_16x16x32_bf16 v[34:37], v[96:99], v[84:87], v[34:37]
	ds_read_b128 v[84:87], v70 offset:42240
	ds_read_b128 v[132:135], v70 offset:42304
	s_waitcnt lgkmcnt(1)
	v_mfma_f32_16x16x32_bf16 v[18:21], v[92:95], v[84:87], v[18:21]
	v_mfma_f32_16x16x32_bf16 v[22:25], v[96:99], v[84:87], v[22:25]
	ds_read_b128 v[84:87], v70 offset:50688
	ds_read_b128 v[136:139], v70 offset:50752
	s_waitcnt lgkmcnt(1)
	v_mfma_f32_16x16x32_bf16 v[6:9], v[92:95], v[84:87], v[6:9]
	v_mfma_f32_16x16x32_bf16 v[10:13], v[96:99], v[84:87], v[10:13]
	ds_read_b128 v[84:87], v70 offset:59136
	ds_read_b128 v[140:143], v70 offset:59200
	v_add_u32_e32 v70, 0x80, v70
	s_waitcnt lgkmcnt(1)
	v_mfma_f32_16x16x32_bf16 v[2:5], v[92:95], v[84:87], v[2:5]
	v_mfma_f32_16x16x32_bf16 v[14:17], v[96:99], v[84:87], v[14:17]
	v_mfma_f32_16x16x32_bf16 v[62:65], v[100:103], v[88:91], v[62:65]
	v_mfma_f32_16x16x32_bf16 v[58:61], v[112:115], v[88:91], v[58:61]
	v_mfma_f32_16x16x32_bf16 v[54:57], v[100:103], v[116:119], v[54:57]
	v_mfma_f32_16x16x32_bf16 v[46:49], v[112:115], v[116:119], v[46:49]
	v_mfma_f32_16x16x32_bf16 v[50:53], v[100:103], v[120:123], v[50:53]
	v_mfma_f32_16x16x32_bf16 v[42:45], v[112:115], v[120:123], v[42:45]
	v_mfma_f32_16x16x32_bf16 v[38:41], v[100:103], v[124:127], v[38:41]
	v_mfma_f32_16x16x32_bf16 v[26:29], v[112:115], v[124:127], v[26:29]
	v_mfma_f32_16x16x32_bf16 v[30:33], v[100:103], v[128:131], v[30:33]
	v_mfma_f32_16x16x32_bf16 v[34:37], v[112:115], v[128:131], v[34:37]
	v_mfma_f32_16x16x32_bf16 v[18:21], v[100:103], v[132:135], v[18:21]
	v_mfma_f32_16x16x32_bf16 v[22:25], v[112:115], v[132:135], v[22:25]
	v_mfma_f32_16x16x32_bf16 v[6:9], v[100:103], v[136:139], v[6:9]
	v_mfma_f32_16x16x32_bf16 v[10:13], v[112:115], v[136:139], v[10:13]
	s_waitcnt lgkmcnt(0)
	v_mfma_f32_16x16x32_bf16 v[2:5], v[100:103], v[140:143], v[2:5]
	v_mfma_f32_16x16x32_bf16 v[14:17], v[112:115], v[140:143], v[14:17]
	v_lshl_add_u64 v[72:73], v[68:69], 0, s[4:5]
	v_add_co_u32_e32 v72, vcc, s25, v72
	v_lshl_add_u64 v[92:93], v[66:67], 0, s[4:5]
	s_nop 0
	v_addc_co_u32_e32 v73, vcc, 0, v73, vcc
	v_add_co_u32_e32 v112, vcc, s25, v92
	ds_read_b128 v[84:87], v70
	ds_read_b128 v[88:91], v70 offset:64
	v_addc_co_u32_e32 v113, vcc, 0, v93, vcc
	v_mov_b32_e32 v92, v216
	v_mov_b32_e32 v93, v217
	v_mov_b32_e32 v94, v218
	v_mov_b32_e32 v95, v219
	v_mov_b32_e32 v96, v220
	v_mov_b32_e32 v97, v221
	v_mov_b32_e32 v98, v222
	v_mov_b32_e32 v99, v223
	v_mov_b32_e32 v100, v224
	v_mov_b32_e32 v101, v225
	v_mov_b32_e32 v102, v226
	v_mov_b32_e32 v103, v227
	s_add_u32 s4, s4, 0x80
	v_mov_b32_e32 v112, v228
	v_mov_b32_e32 v113, v229
	v_mov_b32_e32 v114, v230
	v_mov_b32_e32 v115, v231
	s_addc_u32 s5, s5, 0
	s_cmpk_lg_i32 s4, 0x200
	s_waitcnt lgkmcnt(1)
	v_mfma_f32_16x16x32_bf16 v[62:65], v[92:95], v[84:87], v[62:65]
	v_mfma_f32_16x16x32_bf16 v[58:61], v[96:99], v[84:87], v[58:61]
	ds_read_b128 v[84:87], v70 offset:8448
	ds_read_b128 v[116:119], v70 offset:8512
	s_waitcnt lgkmcnt(1)
	v_mfma_f32_16x16x32_bf16 v[54:57], v[92:95], v[84:87], v[54:57]
	v_mfma_f32_16x16x32_bf16 v[46:49], v[96:99], v[84:87], v[46:49]
	ds_read_b128 v[84:87], v70 offset:16896
	ds_read_b128 v[120:123], v70 offset:16960
	s_waitcnt lgkmcnt(1)
	v_mfma_f32_16x16x32_bf16 v[50:53], v[92:95], v[84:87], v[50:53]
	v_mfma_f32_16x16x32_bf16 v[42:45], v[96:99], v[84:87], v[42:45]
	ds_read_b128 v[84:87], v70 offset:25344
	ds_read_b128 v[124:127], v70 offset:25408
	s_waitcnt lgkmcnt(1)
	v_mfma_f32_16x16x32_bf16 v[38:41], v[92:95], v[84:87], v[38:41]
	v_mfma_f32_16x16x32_bf16 v[26:29], v[96:99], v[84:87], v[26:29]
	ds_read_b128 v[84:87], v70 offset:33792
	ds_read_b128 v[128:131], v70 offset:33856
	s_waitcnt lgkmcnt(1)
	v_mfma_f32_16x16x32_bf16 v[30:33], v[92:95], v[84:87], v[30:33]
	v_mfma_f32_16x16x32_bf16 v[34:37], v[96:99], v[84:87], v[34:37]
	ds_read_b128 v[84:87], v70 offset:42240
	ds_read_b128 v[132:135], v70 offset:42304
	s_waitcnt lgkmcnt(1)
	v_mfma_f32_16x16x32_bf16 v[18:21], v[92:95], v[84:87], v[18:21]
	v_mfma_f32_16x16x32_bf16 v[22:25], v[96:99], v[84:87], v[22:25]
	ds_read_b128 v[84:87], v70 offset:50688
	ds_read_b128 v[136:139], v70 offset:50752
	s_waitcnt lgkmcnt(1)
	v_mfma_f32_16x16x32_bf16 v[6:9], v[92:95], v[84:87], v[6:9]
	v_mfma_f32_16x16x32_bf16 v[10:13], v[96:99], v[84:87], v[10:13]
	ds_read_b128 v[84:87], v70 offset:59136
	ds_read_b128 v[140:143], v70 offset:59200
	v_add_u32_e32 v70, 0x80, v70
	s_waitcnt lgkmcnt(1)
	v_mfma_f32_16x16x32_bf16 v[2:5], v[92:95], v[84:87], v[2:5]
	v_mfma_f32_16x16x32_bf16 v[14:17], v[96:99], v[84:87], v[14:17]
	v_mfma_f32_16x16x32_bf16 v[62:65], v[100:103], v[88:91], v[62:65]
	v_mfma_f32_16x16x32_bf16 v[58:61], v[112:115], v[88:91], v[58:61]
	v_mfma_f32_16x16x32_bf16 v[54:57], v[100:103], v[116:119], v[54:57]
	v_mfma_f32_16x16x32_bf16 v[46:49], v[112:115], v[116:119], v[46:49]
	v_mfma_f32_16x16x32_bf16 v[50:53], v[100:103], v[120:123], v[50:53]
	v_mfma_f32_16x16x32_bf16 v[42:45], v[112:115], v[120:123], v[42:45]
	v_mfma_f32_16x16x32_bf16 v[38:41], v[100:103], v[124:127], v[38:41]
	v_mfma_f32_16x16x32_bf16 v[26:29], v[112:115], v[124:127], v[26:29]
	v_mfma_f32_16x16x32_bf16 v[30:33], v[100:103], v[128:131], v[30:33]
	v_mfma_f32_16x16x32_bf16 v[34:37], v[112:115], v[128:131], v[34:37]
	v_mfma_f32_16x16x32_bf16 v[18:21], v[100:103], v[132:135], v[18:21]
	v_mfma_f32_16x16x32_bf16 v[22:25], v[112:115], v[132:135], v[22:25]
	v_mfma_f32_16x16x32_bf16 v[6:9], v[100:103], v[136:139], v[6:9]
	v_mfma_f32_16x16x32_bf16 v[10:13], v[112:115], v[136:139], v[10:13]
	s_waitcnt lgkmcnt(0)
	v_mfma_f32_16x16x32_bf16 v[2:5], v[100:103], v[140:143], v[2:5]
	v_mfma_f32_16x16x32_bf16 v[14:17], v[112:115], v[140:143], v[14:17]
	s_and_b32 s2, s30, 0xffffff80
	s_add_i32 s31, s31, s16
	v_or_b32_e32 v90, s2, v75
	v_or_b32_e32 v76, s31, v106
	v_mov_b64_e32 v[70:71], s[0:1]
	v_or_b32_e32 v86, 32, v90
	v_lshlrev_b32_e32 v112, 1, v76
	v_mov_b32_e32 v113, v77
	v_mad_i64_i32 v[86:87], s[4:5], v86, s21, v[70:71]
	v_lshl_add_u64 v[88:89], v[86:87], 0, v[112:113]
	v_or_b32_e32 v86, 48, v90
	v_mad_i64_i32 v[86:87], s[4:5], v86, s21, v[70:71]
	v_lshl_add_u64 v[94:95], v[86:87], 0, v[112:113]
	v_or_b32_e32 v86, 64, v90
	v_mad_i64_i32 v[86:87], s[4:5], v86, s21, v[70:71]
	v_lshl_add_u64 v[98:99], v[86:87], 0, v[112:113]
	v_or_b32_e32 v86, 0x50, v90
	v_mad_i64_i32 v[86:87], s[4:5], v86, s21, v[70:71]
	v_lshl_add_u64 v[120:121], v[86:87], 0, v[112:113]
	v_or_b32_e32 v86, 0x60, v90
	v_mad_i64_i32 v[72:73], s[4:5], v90, s21, v[70:71]
	v_lshl_add_u64 v[66:67], v[76:77], 2, s[8:9]
	v_or_b32_e32 v84, 16, v90
	v_mad_i64_i32 v[86:87], s[4:5], v86, s21, v[70:71]
	global_load_dwordx4 v[66:69], v[66:67], off
	v_lshl_add_u64 v[72:73], v[72:73], 0, v[112:113]
	v_mad_i64_i32 v[84:85], s[4:5], v84, s21, v[70:71]
	v_lshl_add_u64 v[122:123], v[86:87], 0, v[112:113]
	v_or_b32_e32 v86, 0x70, v90
	v_lshl_add_u64 v[84:85], v[84:85], 0, v[112:113]
	global_load_dwordx2 v[114:115], v[72:73], off offset:2048
	global_load_dwordx2 v[116:117], v[84:85], off offset:2048
	v_mad_i64_i32 v[70:71], s[4:5], v86, s21, v[70:71]
	v_lshl_add_u64 v[70:71], v[70:71], 0, v[112:113]
	v_or_b32_e32 v76, 16, v76
	global_load_dwordx2 v[118:119], v[88:89], off offset:2048
	global_load_dwordx2 v[100:101], v[94:95], off offset:2048
	global_load_dwordx2 v[96:97], v[98:99], off offset:2048
	global_load_dwordx2 v[92:93], v[120:121], off offset:2048
	global_load_dwordx2 v[90:91], v[122:123], off offset:2048
	global_load_dwordx2 v[86:87], v[70:71], off offset:2048
	global_load_dwordx2 v[124:125], v[84:85], off offset:2080
	global_load_dwordx2 v[126:127], v[72:73], off offset:2080
	global_load_dwordx2 v[102:103], v[94:95], off offset:2080
	global_load_dwordx2 v[128:129], v[88:89], off offset:2080
	s_nop 0
	global_load_dwordx2 v[94:95], v[120:121], off offset:2080
	s_nop 0
	global_load_dwordx2 v[98:99], v[98:99], off offset:2080
	s_nop 0
	global_load_dwordx2 v[84:85], v[70:71], off offset:2080
	global_load_dwordx2 v[88:89], v[122:123], off offset:2080
	v_lshl_add_u64 v[70:71], v[76:77], 2, s[8:9]
	global_load_dwordx4 v[70:73], v[70:71], off
	s_ashr_i32 s4, s29, 2
	s_ashr_i32 s5, s4, 31
	s_lshl_b64 s[4:5], s[4:5], 20
	s_add_u32 s6, s17, s4
	s_addc_u32 s7, s18, s5
	s_lshr_b32 s2, s31, 6
	s_lshl_b64 s[4:5], s[2:3], 14
	s_lshl_b32 s2, s31, 5
	v_lshlrev_b32_e32 v113, 2, v75
	s_and_b32 s2, s2, 0x400
	v_and_b32_e32 v122, 32, v113
	v_lshlrev_b32_e32 v111, 6, v75
	s_add_u32 s4, s6, s4
	s_addc_u32 s5, s7, s5
	s_add_i32 s19, s19, s20
	s_waitcnt vmcnt(16)
	s_nop 0
	v_lshlrev_b32_e32 v120, 16, v114
	v_and_b32_e32 v121, 0xffff0000, v114
	v_pk_mul_f32 v[62:63], v[62:63], v[66:67]
	v_pk_mul_f32 v[64:65], v[64:65], v[68:69]
	v_pk_mul_f32 v[62:63], v[62:63], v[120:121]
	s_waitcnt vmcnt(15)
	s_waitcnt vmcnt(14)
	s_waitcnt vmcnt(13)
	s_waitcnt vmcnt(12)
	s_waitcnt vmcnt(11)
	v_cvt_pk_bf16_f32 v114, v62, v63
	v_lshlrev_b32_e32 v62, 16, v115
	v_and_b32_e32 v63, 0xffff0000, v115
	v_pk_mul_f32 v[62:63], v[64:65], v[62:63]
	s_waitcnt vmcnt(10)
	s_waitcnt vmcnt(9)
	s_waitcnt vmcnt(7)
	s_waitcnt vmcnt(0)
	v_pk_mul_f32 v[58:59], v[58:59], v[70:71]
	v_cvt_pk_bf16_f32 v115, v62, v63
	v_and_or_b32 v62, v112, 24, s2
	v_lshlrev_b32_e32 v112, 16, v126
	v_and_b32_e32 v113, 0xffff0000, v126
	v_pk_mul_f32 v[60:61], v[60:61], v[72:73]
	v_pk_mul_f32 v[58:59], v[58:59], v[112:113]
	v_lshlrev_b32_e32 v112, 16, v127
	v_and_b32_e32 v113, 0xffff0000, v127
	v_pk_mul_f32 v[60:61], v[60:61], v[112:113]
	v_cvt_pk_bf16_f32 v58, v58, v59
	v_cvt_pk_bf16_f32 v59, v60, v61
	v_lshlrev_b32_e32 v60, 1, v76
	v_and_b32_e32 v60, 56, v60
	v_bitop3_b32 v60, v60, v122, v111 bitop3:0x36
	v_or3_b32 v64, v62, v111, v122
	v_or_b32_e32 v76, s2, v60
	global_store_dwordx2 v64, v[114:115], s[4:5]
	global_store_dwordx2 v76, v[58:59], s[4:5]
	v_lshlrev_b32_e32 v58, 16, v116
	v_and_b32_e32 v59, 0xffff0000, v116
	v_pk_mul_f32 v[54:55], v[54:55], v[66:67]
	v_pk_mul_f32 v[56:57], v[56:57], v[68:69]
	v_pk_mul_f32 v[54:55], v[54:55], v[58:59]
	v_lshlrev_b32_e32 v58, 16, v117
	v_and_b32_e32 v59, 0xffff0000, v117
	v_pk_mul_f32 v[56:57], v[56:57], v[58:59]
	v_cvt_pk_bf16_f32 v54, v54, v55
	v_cvt_pk_bf16_f32 v55, v56, v57
	global_store_dwordx2 v64, v[54:55], s[4:5] offset:2048
	v_lshlrev_b32_e32 v54, 16, v124
	v_and_b32_e32 v55, 0xffff0000, v124
	v_pk_mul_f32 v[46:47], v[46:47], v[70:71]
	v_pk_mul_f32 v[48:49], v[48:49], v[72:73]
	v_pk_mul_f32 v[46:47], v[46:47], v[54:55]
	v_lshlrev_b32_e32 v54, 16, v125
	v_and_b32_e32 v55, 0xffff0000, v125
	v_pk_mul_f32 v[48:49], v[48:49], v[54:55]
	v_cvt_pk_bf16_f32 v46, v46, v47
	v_cvt_pk_bf16_f32 v47, v48, v49
	global_store_dwordx2 v76, v[46:47], s[4:5] offset:2048
	v_lshlrev_b32_e32 v46, 16, v118
	v_and_b32_e32 v47, 0xffff0000, v118
	v_pk_mul_f32 v[50:51], v[50:51], v[66:67]
	v_mov_b32_e32 v65, v77
	v_pk_mul_f32 v[48:49], v[52:53], v[68:69]
	v_pk_mul_f32 v[46:47], v[50:51], v[46:47]
	v_lshlrev_b32_e32 v50, 16, v119
	v_and_b32_e32 v51, 0xffff0000, v119
	v_lshl_add_u64 v[62:63], s[4:5], 0, v[64:65]
	v_pk_mul_f32 v[48:49], v[48:49], v[50:51]
	v_cvt_pk_bf16_f32 v46, v46, v47
	v_cvt_pk_bf16_f32 v47, v48, v49
	v_add_co_u32_e32 v48, vcc, s26, v62
	v_pk_mul_f32 v[42:43], v[42:43], v[70:71]
	s_nop 0
	v_addc_co_u32_e32 v49, vcc, 0, v63, vcc
	v_add_co_u32_e32 v50, vcc, s22, v62
	v_pk_mul_f32 v[44:45], v[44:45], v[72:73]
	s_nop 0
	v_addc_co_u32_e32 v51, vcc, 0, v63, vcc
	global_store_dwordx2 v[50:51], v[46:47], off offset:-4096
	v_lshlrev_b32_e32 v46, 16, v128
	v_and_b32_e32 v47, 0xffff0000, v128
	v_pk_mul_f32 v[42:43], v[42:43], v[46:47]
	v_lshlrev_b32_e32 v46, 16, v129
	v_and_b32_e32 v47, 0xffff0000, v129
	v_lshl_add_u64 v[60:61], s[4:5], 0, v[76:77]
	v_pk_mul_f32 v[44:45], v[44:45], v[46:47]
	v_cvt_pk_bf16_f32 v42, v42, v43
	v_cvt_pk_bf16_f32 v43, v44, v45
	v_add_co_u32_e32 v44, vcc, s26, v60
	v_pk_mul_f32 v[38:39], v[38:39], v[66:67]
	s_nop 0
	v_addc_co_u32_e32 v45, vcc, 0, v61, vcc
	v_add_co_u32_e32 v46, vcc, s22, v60
	v_pk_mul_f32 v[40:41], v[40:41], v[68:69]
	s_nop 0
	v_addc_co_u32_e32 v47, vcc, 0, v61, vcc
	global_store_dwordx2 v[46:47], v[42:43], off offset:-4096
	v_lshlrev_b32_e32 v42, 16, v100
	v_and_b32_e32 v43, 0xffff0000, v100
	v_pk_mul_f32 v[38:39], v[38:39], v[42:43]
	v_lshlrev_b32_e32 v42, 16, v101
	v_and_b32_e32 v43, 0xffff0000, v101
	v_pk_mul_f32 v[40:41], v[40:41], v[42:43]
	v_cvt_pk_bf16_f32 v38, v38, v39
	v_cvt_pk_bf16_f32 v39, v40, v41
	global_store_dwordx2 v[48:49], v[38:39], off offset:2048
	v_lshlrev_b32_e32 v38, 16, v102
	v_and_b32_e32 v39, 0xffff0000, v102
	v_pk_mul_f32 v[26:27], v[26:27], v[70:71]
	v_pk_mul_f32 v[28:29], v[28:29], v[72:73]
	v_pk_mul_f32 v[26:27], v[26:27], v[38:39]
	v_lshlrev_b32_e32 v38, 16, v103
	v_and_b32_e32 v39, 0xffff0000, v103
	v_pk_mul_f32 v[28:29], v[28:29], v[38:39]
	v_cvt_pk_bf16_f32 v26, v26, v27
	v_cvt_pk_bf16_f32 v27, v28, v29
	global_store_dwordx2 v[44:45], v[26:27], off offset:2048
	v_lshlrev_b32_e32 v26, 16, v96
	v_and_b32_e32 v27, 0xffff0000, v96
	v_pk_mul_f32 v[30:31], v[30:31], v[66:67]
	v_pk_mul_f32 v[28:29], v[32:33], v[68:69]
	v_pk_mul_f32 v[26:27], v[30:31], v[26:27]
	v_lshlrev_b32_e32 v30, 16, v97
	v_and_b32_e32 v31, 0xffff0000, v97
	v_pk_mul_f32 v[28:29], v[28:29], v[30:31]
	v_cvt_pk_bf16_f32 v26, v26, v27
	v_cvt_pk_bf16_f32 v27, v28, v29
	global_store_dwordx2 v[50:51], v[26:27], off
	v_lshlrev_b32_e32 v26, 16, v98
	v_and_b32_e32 v27, 0xffff0000, v98
	v_pk_mul_f32 v[30:31], v[34:35], v[70:71]
	v_pk_mul_f32 v[28:29], v[36:37], v[72:73]
	v_pk_mul_f32 v[26:27], v[30:31], v[26:27]
	v_lshlrev_b32_e32 v30, 16, v99
	v_and_b32_e32 v31, 0xffff0000, v99
	v_pk_mul_f32 v[28:29], v[28:29], v[30:31]
	v_cvt_pk_bf16_f32 v26, v26, v27
	v_cvt_pk_bf16_f32 v27, v28, v29
	global_store_dwordx2 v[46:47], v[26:27], off
	v_lshlrev_b32_e32 v26, 16, v92
	v_and_b32_e32 v27, 0xffff0000, v92
	v_pk_mul_f32 v[18:19], v[18:19], v[66:67]
	v_pk_mul_f32 v[20:21], v[20:21], v[68:69]
	v_pk_mul_f32 v[18:19], v[18:19], v[26:27]
	v_lshlrev_b32_e32 v26, 16, v93
	v_and_b32_e32 v27, 0xffff0000, v93
	v_pk_mul_f32 v[20:21], v[20:21], v[26:27]
	v_cvt_pk_bf16_f32 v18, v18, v19
	v_cvt_pk_bf16_f32 v19, v20, v21
	global_store_dwordx2 v[50:51], v[18:19], off offset:2048
	v_lshlrev_b32_e32 v18, 16, v94
	v_and_b32_e32 v19, 0xffff0000, v94
	v_pk_mul_f32 v[22:23], v[22:23], v[70:71]
	v_pk_mul_f32 v[20:21], v[24:25], v[72:73]
	v_pk_mul_f32 v[18:19], v[22:23], v[18:19]
	v_lshlrev_b32_e32 v22, 16, v95
	v_and_b32_e32 v23, 0xffff0000, v95
	v_pk_mul_f32 v[20:21], v[20:21], v[22:23]
	v_cvt_pk_bf16_f32 v18, v18, v19
	v_cvt_pk_bf16_f32 v19, v20, v21
	global_store_dwordx2 v[46:47], v[18:19], off offset:2048
	v_lshlrev_b32_e32 v18, 16, v90
	v_and_b32_e32 v19, 0xffff0000, v90
	v_pk_mul_f32 v[6:7], v[6:7], v[66:67]
	v_pk_mul_f32 v[8:9], v[8:9], v[68:69]
	v_pk_mul_f32 v[6:7], v[6:7], v[18:19]
	v_lshlrev_b32_e32 v18, 16, v91
	v_and_b32_e32 v19, 0xffff0000, v91
	v_pk_mul_f32 v[8:9], v[8:9], v[18:19]
	v_cvt_pk_bf16_f32 v6, v6, v7
	v_cvt_pk_bf16_f32 v7, v8, v9
	v_add_co_u32_e32 v8, vcc, s27, v62
	v_pk_mul_f32 v[10:11], v[10:11], v[70:71]
	s_nop 0
	v_addc_co_u32_e32 v9, vcc, 0, v63, vcc
	global_store_dwordx2 v[8:9], v[6:7], off
	v_lshlrev_b32_e32 v6, 16, v88
	v_and_b32_e32 v7, 0xffff0000, v88
	v_pk_mul_f32 v[12:13], v[12:13], v[72:73]
	v_pk_mul_f32 v[6:7], v[10:11], v[6:7]
	v_lshlrev_b32_e32 v10, 16, v89
	v_and_b32_e32 v11, 0xffff0000, v89
	v_pk_mul_f32 v[10:11], v[12:13], v[10:11]
	v_cvt_pk_bf16_f32 v6, v6, v7
	v_cvt_pk_bf16_f32 v7, v10, v11
	v_add_co_u32_e32 v10, vcc, s27, v60
	v_pk_mul_f32 v[2:3], v[2:3], v[66:67]
	s_nop 0
	v_addc_co_u32_e32 v11, vcc, 0, v61, vcc
	global_store_dwordx2 v[10:11], v[6:7], off
	v_lshlrev_b32_e32 v6, 16, v86
	v_and_b32_e32 v7, 0xffff0000, v86
	v_pk_mul_f32 v[4:5], v[4:5], v[68:69]
	v_pk_mul_f32 v[2:3], v[2:3], v[6:7]
	v_lshlrev_b32_e32 v6, 16, v87
	v_and_b32_e32 v7, 0xffff0000, v87
	v_pk_mul_f32 v[4:5], v[4:5], v[6:7]
	v_cvt_pk_bf16_f32 v2, v2, v3
	v_cvt_pk_bf16_f32 v3, v4, v5
	global_store_dwordx2 v[8:9], v[2:3], off offset:2048
	v_lshlrev_b32_e32 v2, 16, v84
	v_and_b32_e32 v3, 0xffff0000, v84
	v_pk_mul_f32 v[6:7], v[14:15], v[70:71]
	v_pk_mul_f32 v[4:5], v[16:17], v[72:73]
	v_pk_mul_f32 v[2:3], v[6:7], v[2:3]
	v_lshlrev_b32_e32 v6, 16, v85
	v_and_b32_e32 v7, 0xffff0000, v85
	v_readlane_b32 s4, v249, 34
	v_pk_mul_f32 v[4:5], v[4:5], v[6:7]
	s_add_i32 s29, s29, s4
	s_add_i32 s28, s28, s4
	v_cvt_pk_bf16_f32 v2, v2, v3
	v_cvt_pk_bf16_f32 v3, v4, v5
	s_cmpk_gt_i32 s29, 0xff
	v_readlane_b32 s5, v249, 35
	global_store_dwordx2 v[10:11], v[2:3], off offset:2048
	s_cbranch_scc0 .LBB0_1368
